# v11 + nt hint on UP-projection write-through H stores
# baseline (speedup 1.0000x reference)
; #define PG8_LAS __attribute__((address_space(3)))
; __device__ __forceinline__ unsigned cvtpk(float lo, float hi) { f32x2_t v = {lo, hi}; f16x2_t b = __builtin_convertvector(v, f16x2_t); return __builtin_bit_cast(unsigned, b); }
;     __device__ __forceinline__ void operator()(const f32x4 (&acc)[2][2][4][2], const Unit& u, int wr, int wc, int fr, int fq) const {
;         const int row0 = u.pm * BM + wr * 64 + fr, col0 = u.pn * BM + wc * 32 + 8 * fq;
;         float rs[2][4]; const PG8_LAS float* tb = rsl + (u.pm == pmA ? 0 : 256);
; #pragma unroll
;         for (int ai = 0; ai < 2; ++ai)
; #pragma unroll
;             for (int m = 0; m < 4; ++m) rs[ai][m] = tb[ai * HALF + wr * 64 + m * 16 + fr];
; #pragma unroll
;         for (int ai = 0; ai < 2; ++ai)
; #pragma unroll
;             for (int m = 0; m < 4; ++m) { const int row = row0 + ai * HALF + m * 16; bf16_t* rowp = H + (size_t)row * 4096 + col0;
; #pragma unroll
;                 for (int bj = 0; bj < 2; ++bj) { f32x4 v0 = acc[ai][bj][m][0] * rs[ai][m], v1 = acc[ai][bj][m][1] * rs[ai][m];
; #pragma unroll
;                     for (int e = 0; e < 4; ++e) { const float a = fmaxf(v0[e], 0.f), b = fmaxf(v1[e], 0.f); v0[e] = a * a; v1[e] = b * b; }
;                     u32x4 w; w.x = cvtpk(v0[0], v0[1]); w.y = cvtpk(v0[2], v0[3]); w.z = cvtpk(v1[0], v1[1]); w.w = cvtpk(v1[2], v1[3]);
;                     *(u32x4*)(rowp + bj * HALF) = w; } }
.LBB0_970:
	v_readlane_b32 s21, v255, 57
	s_cmp_eq_u32 s42, s21
	s_cselect_b32 s21, 0, 0x400
	v_add_u32_e32 v140, s21, v153
	v_lshl_add_u32 v148, s42, 8, v151
	ds_read2_b32 v[156:157], v140 offset1:16
	ds_read2_b32 v[146:147], v140 offset0:32 offset1:48
	ds_read2_b32 v[144:145], v140 offset0:128 offset1:144
	ds_read2_b32 v[142:143], v140 offset0:160 offset1:176
	v_lshl_or_b32 v140, s53, 8, v154
	v_ashrrev_i32_e32 v149, 31, v148
	v_ashrrev_i32_e32 v141, 31, v140
	v_lshlrev_b64 v[158:159], 13, v[148:149]
	s_waitcnt lgkmcnt(0)
	v_pk_mul_f32 v[122:123], v[122:123], v[156:157] op_sel_hi:[1,0]
	v_lshl_add_u64 v[158:159], s[74:75], 0, v[158:159]
	v_lshlrev_b64 v[160:161], 1, v[140:141]
	v_pk_mul_f32 v[128:129], v[128:129], v[156:157] op_sel_hi:[1,0]
	v_pk_mul_f32 v[126:127], v[126:127], v[156:157] op_sel_hi:[1,0]
	v_pk_mul_f32 v[124:125], v[124:125], v[156:157] op_sel_hi:[1,0]
	v_max_f32_e32 v122, 0, v122
	v_max_f32_e32 v123, 0, v123
	v_lshl_add_u64 v[140:141], v[158:159], 0, v[160:161]
	v_max_f32_e32 v126, 0, v126
	v_max_f32_e32 v127, 0, v127
	v_pk_mul_f32 v[158:159], v[122:123], v[122:123]
	v_max_f32_e32 v122, 0, v128
	v_max_f32_e32 v124, 0, v124
	v_max_f32_e32 v123, 0, v129
	v_max_f32_e32 v125, 0, v125
	v_pk_mul_f32 v[126:127], v[126:127], v[126:127]
	v_pk_mul_f32 v[128:129], v[122:123], v[122:123]
	v_pk_mul_f32 v[172:173], v[124:125], v[124:125]
	v_pk_mul_f32 v[114:115], v[114:115], v[156:157] op_sel_hi:[1,0]
	v_cvt_pk_f16_f32 v122, v126, v127
	v_cvt_pk_f16_f32 v123, v128, v129
	v_cvt_pk_f16_f32 v124, v158, v159
	v_cvt_pk_f16_f32 v125, v172, v173
	v_pk_mul_f32 v[120:121], v[120:121], v[156:157] op_sel_hi:[1,0]
	v_pk_mul_f32 v[118:119], v[118:119], v[156:157] op_sel_hi:[1,0]
	v_pk_mul_f32 v[116:117], v[116:117], v[156:157] op_sel_hi:[1,0]
	v_max_f32_e32 v114, 0, v114
	v_max_f32_e32 v115, 0, v115
	global_store_dwordx4 v[140:141], v[122:125], off sc1 nt
	v_max_f32_e32 v118, 0, v118
	v_max_f32_e32 v119, 0, v119
	v_pk_mul_f32 v[122:123], v[114:115], v[114:115]
	v_max_f32_e32 v114, 0, v120
	v_max_f32_e32 v116, 0, v116
	v_max_f32_e32 v115, 0, v121
	v_max_f32_e32 v117, 0, v117
	v_pk_mul_f32 v[118:119], v[118:119], v[118:119]
	v_pk_mul_f32 v[120:121], v[114:115], v[114:115]
	v_pk_mul_f32 v[124:125], v[116:117], v[116:117]
	v_cvt_pk_f16_f32 v114, v118, v119
	v_cvt_pk_f16_f32 v115, v120, v121
	v_cvt_pk_f16_f32 v116, v122, v123
	v_cvt_pk_f16_f32 v117, v124, v125
	global_store_dwordx4 v[140:141], v[114:117], off offset:256 sc1 nt
	v_pk_mul_f32 v[90:91], v[90:91], v[146:147] op_sel_hi:[1,0]
	v_pk_mul_f32 v[96:97], v[96:97], v[146:147] op_sel_hi:[1,0]
	v_mov_b32_e32 v116, v157
	v_or_b32_e32 v114, 16, v148
	v_pk_mul_f32 v[106:107], v[106:107], v[116:117] op_sel_hi:[1,0]
	v_ashrrev_i32_e32 v115, 31, v114
	v_pk_mul_f32 v[112:113], v[112:113], v[116:117] op_sel_hi:[1,0]
	v_pk_mul_f32 v[110:111], v[110:111], v[116:117] op_sel_hi:[1,0]
	v_pk_mul_f32 v[108:109], v[108:109], v[116:117] op_sel_hi:[1,0]
	v_max_f32_e32 v106, 0, v106
	v_max_f32_e32 v107, 0, v107
	v_lshlrev_b64 v[114:115], 13, v[114:115]
	v_max_f32_e32 v110, 0, v110
	v_max_f32_e32 v111, 0, v111
	v_pk_mul_f32 v[118:119], v[106:107], v[106:107]
	v_max_f32_e32 v106, 0, v112
	v_max_f32_e32 v108, 0, v108
	v_max_f32_e32 v107, 0, v113
	v_max_f32_e32 v109, 0, v109
	v_lshl_add_u64 v[114:115], s[74:75], 0, v[114:115]
	v_pk_mul_f32 v[110:111], v[110:111], v[110:111]
	v_pk_mul_f32 v[112:113], v[106:107], v[106:107]
	v_pk_mul_f32 v[120:121], v[108:109], v[108:109]
	v_pk_mul_f32 v[98:99], v[98:99], v[116:117] op_sel_hi:[1,0]
	v_lshl_add_u64 v[114:115], v[114:115], 0, v[160:161]
	v_cvt_pk_f16_f32 v106, v110, v111
	v_cvt_pk_f16_f32 v107, v112, v113
	v_cvt_pk_f16_f32 v108, v118, v119
	v_cvt_pk_f16_f32 v109, v120, v121
	v_pk_mul_f32 v[104:105], v[104:105], v[116:117] op_sel_hi:[1,0]
	v_pk_mul_f32 v[102:103], v[102:103], v[116:117] op_sel_hi:[1,0]
	v_pk_mul_f32 v[100:101], v[100:101], v[116:117] op_sel_hi:[1,0]
	v_max_f32_e32 v98, 0, v98
	v_max_f32_e32 v99, 0, v99
	global_store_dwordx4 v[114:115], v[106:109], off sc1 nt
	v_max_f32_e32 v102, 0, v102
	v_max_f32_e32 v103, 0, v103
	v_pk_mul_f32 v[106:107], v[98:99], v[98:99]
	v_max_f32_e32 v98, 0, v104
	v_max_f32_e32 v100, 0, v100
	v_max_f32_e32 v99, 0, v105
	v_max_f32_e32 v101, 0, v101
	v_pk_mul_f32 v[102:103], v[102:103], v[102:103]
	v_pk_mul_f32 v[104:105], v[98:99], v[98:99]
	v_pk_mul_f32 v[108:109], v[100:101], v[100:101]
	v_cvt_pk_f16_f32 v98, v102, v103
	v_cvt_pk_f16_f32 v99, v104, v105
	v_cvt_pk_f16_f32 v100, v106, v107
	v_cvt_pk_f16_f32 v101, v108, v109
	global_store_dwordx4 v[114:115], v[98:101], off offset:256 sc1 nt
	v_pk_mul_f32 v[94:95], v[94:95], v[146:147] op_sel_hi:[1,0]
	v_pk_mul_f32 v[92:93], v[92:93], v[146:147] op_sel_hi:[1,0]
	v_or_b32_e32 v98, 32, v148
	v_ashrrev_i32_e32 v99, 31, v98
	v_max_f32_e32 v90, 0, v90
	v_max_f32_e32 v91, 0, v91
	v_lshlrev_b64 v[98:99], 13, v[98:99]
	v_max_f32_e32 v94, 0, v94
	v_max_f32_e32 v95, 0, v95
	v_pk_mul_f32 v[100:101], v[90:91], v[90:91]
	v_max_f32_e32 v90, 0, v96
	v_max_f32_e32 v92, 0, v92
	v_max_f32_e32 v91, 0, v97
	v_max_f32_e32 v93, 0, v93
	v_lshl_add_u64 v[98:99], s[74:75], 0, v[98:99]
	v_pk_mul_f32 v[94:95], v[94:95], v[94:95]
	v_pk_mul_f32 v[96:97], v[90:91], v[90:91]
	v_pk_mul_f32 v[102:103], v[92:93], v[92:93]
	v_pk_mul_f32 v[82:83], v[82:83], v[146:147] op_sel_hi:[1,0]
	v_lshl_add_u64 v[98:99], v[98:99], 0, v[160:161]
	v_cvt_pk_f16_f32 v90, v94, v95
	v_cvt_pk_f16_f32 v91, v96, v97
	v_cvt_pk_f16_f32 v92, v100, v101
	v_cvt_pk_f16_f32 v93, v102, v103
	v_pk_mul_f32 v[88:89], v[88:89], v[146:147] op_sel_hi:[1,0]
	v_pk_mul_f32 v[86:87], v[86:87], v[146:147] op_sel_hi:[1,0]
	v_pk_mul_f32 v[84:85], v[84:85], v[146:147] op_sel_hi:[1,0]
; __device__ __forceinline__ unsigned cvtpk(float lo, float hi) { f32x2_t v = {lo, hi}; f16x2_t b = __builtin_convertvector(v, f16x2_t); return __builtin_bit_cast(unsigned, b); }
;     __device__ __forceinline__ void operator()(const f32x4 (&acc)[2][2][4][2], const Unit& u, int wr, int wc, int fr, int fq) const {
;     ...
; #pragma unroll
;         for (int ai = 0; ai < 2; ++ai)
; #pragma unroll
;             for (int m = 0; m < 4; ++m) { const int row = row0 + ai * HALF + m * 16; bf16_t* rowp = H + (size_t)row * 4096 + col0;
; #pragma unroll
;                 for (int bj = 0; bj < 2; ++bj) { f32x4 v0 = acc[ai][bj][m][0] * rs[ai][m], v1 = acc[ai][bj][m][1] * rs[ai][m];
; #pragma unroll
;                     for (int e = 0; e < 4; ++e) { const float a = fmaxf(v0[e], 0.f), b = fmaxf(v1[e], 0.f); v0[e] = a * a; v1[e] = b * b; }
;                     u32x4 w; w.x = cvtpk(v0[0], v0[1]); w.y = cvtpk(v0[2], v0[3]); w.z = cvtpk(v1[0], v1[1]); w.w = cvtpk(v1[2], v1[3]);
;                     *(u32x4*)(rowp + bj * HALF) = w; } }
	v_max_f32_e32 v82, 0, v82
	v_max_f32_e32 v83, 0, v83
	global_store_dwordx4 v[98:99], v[90:93], off sc1 nt
	v_max_f32_e32 v86, 0, v86
	v_max_f32_e32 v87, 0, v87
	v_pk_mul_f32 v[90:91], v[82:83], v[82:83]
	v_max_f32_e32 v82, 0, v88
	v_max_f32_e32 v84, 0, v84
	v_max_f32_e32 v83, 0, v89
	v_max_f32_e32 v85, 0, v85
	v_pk_mul_f32 v[86:87], v[86:87], v[86:87]
	v_pk_mul_f32 v[88:89], v[82:83], v[82:83]
	v_pk_mul_f32 v[92:93], v[84:85], v[84:85]
	v_cvt_pk_f16_f32 v82, v86, v87
	v_cvt_pk_f16_f32 v83, v88, v89
	v_cvt_pk_f16_f32 v84, v90, v91
	v_cvt_pk_f16_f32 v85, v92, v93
	global_store_dwordx4 v[98:99], v[82:85], off offset:256 sc1 nt
	v_pk_mul_f32 v[62:63], v[62:63], v[144:145] op_sel_hi:[1,0]
	v_pk_mul_f32 v[58:59], v[58:59], v[144:145] op_sel_hi:[1,0]
	v_mov_b32_e32 v84, v147
	v_or_b32_e32 v82, 48, v148
	v_pk_mul_f32 v[74:75], v[74:75], v[84:85] op_sel_hi:[1,0]
	v_ashrrev_i32_e32 v83, 31, v82
	v_pk_mul_f32 v[80:81], v[80:81], v[84:85] op_sel_hi:[1,0]
	v_pk_mul_f32 v[78:79], v[78:79], v[84:85] op_sel_hi:[1,0]
	v_pk_mul_f32 v[76:77], v[76:77], v[84:85] op_sel_hi:[1,0]
	v_max_f32_e32 v74, 0, v74
	v_max_f32_e32 v75, 0, v75
	v_lshlrev_b64 v[82:83], 13, v[82:83]
	v_max_f32_e32 v78, 0, v78
	v_max_f32_e32 v79, 0, v79
	v_pk_mul_f32 v[86:87], v[74:75], v[74:75]
	v_max_f32_e32 v74, 0, v80
	v_max_f32_e32 v76, 0, v76
	v_max_f32_e32 v75, 0, v81
	v_max_f32_e32 v77, 0, v77
	v_lshl_add_u64 v[82:83], s[74:75], 0, v[82:83]
	v_pk_mul_f32 v[78:79], v[78:79], v[78:79]
	v_pk_mul_f32 v[80:81], v[74:75], v[74:75]
	v_pk_mul_f32 v[88:89], v[76:77], v[76:77]
	v_pk_mul_f32 v[66:67], v[66:67], v[84:85] op_sel_hi:[1,0]
	v_lshl_add_u64 v[82:83], v[82:83], 0, v[160:161]
	v_cvt_pk_f16_f32 v74, v78, v79
	v_cvt_pk_f16_f32 v75, v80, v81
	v_cvt_pk_f16_f32 v76, v86, v87
	v_cvt_pk_f16_f32 v77, v88, v89
	v_pk_mul_f32 v[72:73], v[72:73], v[84:85] op_sel_hi:[1,0]
	v_pk_mul_f32 v[70:71], v[70:71], v[84:85] op_sel_hi:[1,0]
	v_pk_mul_f32 v[68:69], v[68:69], v[84:85] op_sel_hi:[1,0]
	v_max_f32_e32 v66, 0, v66
	v_max_f32_e32 v67, 0, v67
	global_store_dwordx4 v[82:83], v[74:77], off sc1 nt
	v_max_f32_e32 v70, 0, v70
	v_max_f32_e32 v71, 0, v71
	v_pk_mul_f32 v[74:75], v[66:67], v[66:67]
	v_max_f32_e32 v66, 0, v72
	v_max_f32_e32 v68, 0, v68
	v_max_f32_e32 v67, 0, v73
	v_max_f32_e32 v69, 0, v69
	v_pk_mul_f32 v[70:71], v[70:71], v[70:71]
	v_pk_mul_f32 v[72:73], v[66:67], v[66:67]
	v_pk_mul_f32 v[76:77], v[68:69], v[68:69]
	v_cvt_pk_f16_f32 v66, v70, v71
	v_cvt_pk_f16_f32 v67, v72, v73
	v_cvt_pk_f16_f32 v68, v74, v75
	v_cvt_pk_f16_f32 v69, v76, v77
	v_pk_mul_f32 v[64:65], v[64:65], v[144:145] op_sel_hi:[1,0]
	v_pk_mul_f32 v[60:61], v[60:61], v[144:145] op_sel_hi:[1,0]
	v_max_f32_e32 v62, 0, v62
	v_max_f32_e32 v58, 0, v58
	v_max_f32_e32 v63, 0, v63
	v_max_f32_e32 v59, 0, v59
	global_store_dwordx4 v[82:83], v[66:69], off offset:256 sc1 nt
	v_pk_mul_f32 v[62:63], v[62:63], v[62:63]
	v_max_f32_e32 v60, 0, v60
	v_pk_mul_f32 v[68:69], v[58:59], v[58:59]
	v_max_f32_e32 v58, 0, v64
	v_max_f32_e32 v59, 0, v65
	v_max_f32_e32 v61, 0, v61
	s_mov_b32 s21, 0x100000
	v_pk_mul_f32 v[64:65], v[58:59], v[58:59]
	v_pk_mul_f32 v[70:71], v[60:61], v[60:61]
	v_cvt_pk_f16_f32 v58, v62, v63
	v_add_co_u32_e32 v62, vcc, s21, v140
	v_pk_mul_f32 v[50:51], v[50:51], v[144:145] op_sel_hi:[1,0]
	v_cvt_pk_f16_f32 v59, v64, v65
	v_cvt_pk_f16_f32 v60, v68, v69
	v_cvt_pk_f16_f32 v61, v70, v71
	v_addc_co_u32_e32 v63, vcc, 0, v141, vcc
	v_pk_mul_f32 v[56:57], v[56:57], v[144:145] op_sel_hi:[1,0]
	v_pk_mul_f32 v[54:55], v[54:55], v[144:145] op_sel_hi:[1,0]
	v_pk_mul_f32 v[52:53], v[52:53], v[144:145] op_sel_hi:[1,0]
	v_max_f32_e32 v50, 0, v50
	v_max_f32_e32 v51, 0, v51
	global_store_dwordx4 v[62:63], v[58:61], off sc1 nt
	v_max_f32_e32 v54, 0, v54
	v_max_f32_e32 v55, 0, v55
	v_pk_mul_f32 v[58:59], v[50:51], v[50:51]
	v_max_f32_e32 v50, 0, v56
	v_max_f32_e32 v52, 0, v52
	v_max_f32_e32 v51, 0, v57
	v_max_f32_e32 v53, 0, v53
	s_mov_b64 s[26:27], 0x100000
	v_pk_mul_f32 v[54:55], v[54:55], v[54:55]
	v_pk_mul_f32 v[56:57], v[50:51], v[50:51]
	v_pk_mul_f32 v[60:61], v[52:53], v[52:53]
	v_lshl_add_u64 v[66:67], v[140:141], 0, s[26:27]
	v_cvt_pk_f16_f32 v50, v54, v55
	v_cvt_pk_f16_f32 v51, v56, v57
	v_cvt_pk_f16_f32 v52, v58, v59
	v_cvt_pk_f16_f32 v53, v60, v61
	global_store_dwordx4 v[66:67], v[50:53], off offset:256 sc1 nt
	s_mov_b32 s21, 0x120000
	s_mov_b64 s[26:27], 0x120000
	v_mov_b32_e32 v52, v145
	v_pk_mul_f32 v[46:47], v[46:47], v[52:53] op_sel_hi:[1,0]
	v_pk_mul_f32 v[42:43], v[42:43], v[52:53] op_sel_hi:[1,0]
	v_pk_mul_f32 v[48:49], v[48:49], v[52:53] op_sel_hi:[1,0]
	v_pk_mul_f32 v[44:45], v[44:45], v[52:53] op_sel_hi:[1,0]
	v_max_f32_e32 v46, 0, v46
	v_max_f32_e32 v42, 0, v42
	v_max_f32_e32 v47, 0, v47
	v_max_f32_e32 v43, 0, v43
	v_pk_mul_f32 v[46:47], v[46:47], v[46:47]
	v_pk_mul_f32 v[54:55], v[42:43], v[42:43]
	v_max_f32_e32 v42, 0, v48
	v_max_f32_e32 v44, 0, v44
	v_max_f32_e32 v43, 0, v49
	v_max_f32_e32 v45, 0, v45
	v_pk_mul_f32 v[48:49], v[42:43], v[42:43]
	v_pk_mul_f32 v[56:57], v[44:45], v[44:45]
	v_cvt_pk_f16_f32 v42, v46, v47
; __device__ __forceinline__ unsigned cvtpk(float lo, float hi) { f32x2_t v = {lo, hi}; f16x2_t b = __builtin_convertvector(v, f16x2_t); return __builtin_bit_cast(unsigned, b); }
; #define PG8_BAR __builtin_amdgcn_s_barrier()
;     __device__ __forceinline__ void operator()(const f32x4 (&acc)[2][2][4][2], const Unit& u, int wr, int wc, int fr, int fq) const {
;     ...
; #pragma unroll
;         for (int ai = 0; ai < 2; ++ai)
; #pragma unroll
;             for (int m = 0; m < 4; ++m) { const int row = row0 + ai * HALF + m * 16; bf16_t* rowp = H + (size_t)row * 4096 + col0;
; #pragma unroll
;                 for (int bj = 0; bj < 2; ++bj) { f32x4 v0 = acc[ai][bj][m][0] * rs[ai][m], v1 = acc[ai][bj][m][1] * rs[ai][m];
; #pragma unroll
;                     for (int e = 0; e < 4; ++e) { const float a = fmaxf(v0[e], 0.f), b = fmaxf(v1[e], 0.f); v0[e] = a * a; v1[e] = b * b; }
;                     u32x4 w; w.x = cvtpk(v0[0], v0[1]); w.y = cvtpk(v0[2], v0[3]); w.z = cvtpk(v1[0], v1[1]); w.w = cvtpk(v1[2], v1[3]);
;                     *(u32x4*)(rowp + bj * HALF) = w; } }
; template <class Epi, class Sched, bool ALIGN_EPI = false, bool SP2 = false>
; __device__ __forceinline__ void gemm_phase(PG8_LAS unsigned char* lds, const Gemm g, const Sched& S, const Epi& E) {
;     ...
;         if (!has_next) break;
; #pragma unroll
;         for (int a = 0; a < 2; ++a)
; #pragma unroll
;             for (int b = 0; b < 2; ++b)
; #pragma unroll
;                 for (int m = 0; m < 4; ++m)
; #pragma unroll
;                     for (int n = 0; n < 2; ++n) acc[a][b][m][n] = (f32x4){0.f, 0.f, 0.f, 0.f};
;         cur = nxt; cA = nA; cB = nB; ++ui;
;         if constexpr (ALIGN_EPI) { if (wr == 1) PG8_BAR; }
	v_add_co_u32_e32 v46, vcc, s21, v140
	v_pk_mul_f32 v[34:35], v[34:35], v[52:53] op_sel_hi:[1,0]
	v_cvt_pk_f16_f32 v43, v48, v49
	v_cvt_pk_f16_f32 v44, v54, v55
	v_cvt_pk_f16_f32 v45, v56, v57
	v_addc_co_u32_e32 v47, vcc, 0, v141, vcc
	v_pk_mul_f32 v[40:41], v[40:41], v[52:53] op_sel_hi:[1,0]
	v_pk_mul_f32 v[38:39], v[38:39], v[52:53] op_sel_hi:[1,0]
	v_pk_mul_f32 v[36:37], v[36:37], v[52:53] op_sel_hi:[1,0]
	v_max_f32_e32 v34, 0, v34
	v_max_f32_e32 v35, 0, v35
	global_store_dwordx4 v[46:47], v[42:45], off sc1 nt
	v_max_f32_e32 v38, 0, v38
	v_max_f32_e32 v39, 0, v39
	v_pk_mul_f32 v[42:43], v[34:35], v[34:35]
	v_max_f32_e32 v34, 0, v40
	v_max_f32_e32 v36, 0, v36
	v_max_f32_e32 v35, 0, v41
	v_max_f32_e32 v37, 0, v37
	v_pk_mul_f32 v[38:39], v[38:39], v[38:39]
	v_pk_mul_f32 v[40:41], v[34:35], v[34:35]
	v_pk_mul_f32 v[44:45], v[36:37], v[36:37]
	v_pk_mul_f32 v[30:31], v[30:31], v[142:143] op_sel_hi:[1,0]
	v_pk_mul_f32 v[26:27], v[26:27], v[142:143] op_sel_hi:[1,0]
	v_lshl_add_u64 v[50:51], v[140:141], 0, s[26:27]
	v_cvt_pk_f16_f32 v34, v38, v39
	v_cvt_pk_f16_f32 v35, v40, v41
	v_cvt_pk_f16_f32 v36, v42, v43
	v_cvt_pk_f16_f32 v37, v44, v45
	v_pk_mul_f32 v[32:33], v[32:33], v[142:143] op_sel_hi:[1,0]
	v_pk_mul_f32 v[28:29], v[28:29], v[142:143] op_sel_hi:[1,0]
	v_max_f32_e32 v30, 0, v30
	v_max_f32_e32 v26, 0, v26
	v_max_f32_e32 v31, 0, v31
	v_max_f32_e32 v27, 0, v27
	global_store_dwordx4 v[50:51], v[34:37], off offset:256 sc1 nt
	v_pk_mul_f32 v[30:31], v[30:31], v[30:31]
	v_max_f32_e32 v28, 0, v28
	v_pk_mul_f32 v[36:37], v[26:27], v[26:27]
	v_max_f32_e32 v26, 0, v32
	v_max_f32_e32 v27, 0, v33
	v_max_f32_e32 v29, 0, v29
	s_mov_b32 s21, 0x140000
	v_pk_mul_f32 v[32:33], v[26:27], v[26:27]
	v_pk_mul_f32 v[38:39], v[28:29], v[28:29]
	v_cvt_pk_f16_f32 v26, v30, v31
	v_add_co_u32_e32 v30, vcc, s21, v140
	v_pk_mul_f32 v[18:19], v[18:19], v[142:143] op_sel_hi:[1,0]
	v_cvt_pk_f16_f32 v27, v32, v33
	v_cvt_pk_f16_f32 v28, v36, v37
	v_cvt_pk_f16_f32 v29, v38, v39
	v_addc_co_u32_e32 v31, vcc, 0, v141, vcc
	v_pk_mul_f32 v[24:25], v[24:25], v[142:143] op_sel_hi:[1,0]
	v_pk_mul_f32 v[22:23], v[22:23], v[142:143] op_sel_hi:[1,0]
	v_pk_mul_f32 v[20:21], v[20:21], v[142:143] op_sel_hi:[1,0]
	v_max_f32_e32 v18, 0, v18
	v_max_f32_e32 v19, 0, v19
	global_store_dwordx4 v[30:31], v[26:29], off sc1 nt
	v_max_f32_e32 v22, 0, v22
	v_max_f32_e32 v23, 0, v23
	v_pk_mul_f32 v[26:27], v[18:19], v[18:19]
	v_max_f32_e32 v18, 0, v24
	v_max_f32_e32 v20, 0, v20
	v_max_f32_e32 v19, 0, v25
	v_max_f32_e32 v21, 0, v21
	s_mov_b64 s[26:27], 0x140000
	v_pk_mul_f32 v[22:23], v[22:23], v[22:23]
	v_pk_mul_f32 v[24:25], v[18:19], v[18:19]
	v_pk_mul_f32 v[28:29], v[20:21], v[20:21]
	v_lshl_add_u64 v[34:35], v[140:141], 0, s[26:27]
	v_cvt_pk_f16_f32 v18, v22, v23
	v_cvt_pk_f16_f32 v19, v24, v25
	v_cvt_pk_f16_f32 v20, v26, v27
	v_cvt_pk_f16_f32 v21, v28, v29
	global_store_dwordx4 v[34:35], v[18:21], off offset:256 sc1 nt
	s_mov_b32 s21, 0x160000
	s_mov_b64 s[26:27], 0x160000
	v_mov_b32_e32 v20, v143
	v_pk_mul_f32 v[14:15], v[14:15], v[20:21] op_sel_hi:[1,0]
	v_pk_mul_f32 v[10:11], v[10:11], v[20:21] op_sel_hi:[1,0]
	v_pk_mul_f32 v[16:17], v[16:17], v[20:21] op_sel_hi:[1,0]
	v_pk_mul_f32 v[12:13], v[12:13], v[20:21] op_sel_hi:[1,0]
	v_max_f32_e32 v14, 0, v14
	v_max_f32_e32 v10, 0, v10
	v_max_f32_e32 v15, 0, v15
	v_max_f32_e32 v11, 0, v11
	v_pk_mul_f32 v[14:15], v[14:15], v[14:15]
	v_pk_mul_f32 v[22:23], v[10:11], v[10:11]
	v_max_f32_e32 v10, 0, v16
	v_max_f32_e32 v12, 0, v12
	v_max_f32_e32 v11, 0, v17
	v_max_f32_e32 v13, 0, v13
	v_pk_mul_f32 v[16:17], v[10:11], v[10:11]
	v_pk_mul_f32 v[24:25], v[12:13], v[12:13]
	v_cvt_pk_f16_f32 v10, v14, v15
	v_add_co_u32_e32 v14, vcc, s21, v140
	v_pk_mul_f32 v[2:3], v[2:3], v[20:21] op_sel_hi:[1,0]
	v_cvt_pk_f16_f32 v11, v16, v17
	v_cvt_pk_f16_f32 v12, v22, v23
	v_cvt_pk_f16_f32 v13, v24, v25
	v_addc_co_u32_e32 v15, vcc, 0, v141, vcc
	v_pk_mul_f32 v[8:9], v[8:9], v[20:21] op_sel_hi:[1,0]
	v_pk_mul_f32 v[6:7], v[6:7], v[20:21] op_sel_hi:[1,0]
	v_pk_mul_f32 v[4:5], v[4:5], v[20:21] op_sel_hi:[1,0]
	v_max_f32_e32 v2, 0, v2
	v_max_f32_e32 v3, 0, v3
	global_store_dwordx4 v[14:15], v[10:13], off sc1 nt
	v_max_f32_e32 v6, 0, v6
	v_max_f32_e32 v7, 0, v7
	v_pk_mul_f32 v[10:11], v[2:3], v[2:3]
	v_max_f32_e32 v2, 0, v8
	v_max_f32_e32 v4, 0, v4
	v_max_f32_e32 v3, 0, v9
	v_max_f32_e32 v5, 0, v5
	v_pk_mul_f32 v[6:7], v[6:7], v[6:7]
	v_pk_mul_f32 v[8:9], v[2:3], v[2:3]
	v_pk_mul_f32 v[12:13], v[4:5], v[4:5]
	v_readlane_b32 s76, v253, 5
	v_lshl_add_u64 v[18:19], v[140:141], 0, s[26:27]
	v_cvt_pk_f16_f32 v2, v6, v7
	v_cvt_pk_f16_f32 v3, v8, v9
	v_cvt_pk_f16_f32 v4, v10, v11
	v_cvt_pk_f16_f32 v5, v12, v13
	s_andn2_b64 vcc, exec, s[38:39]
	s_mov_b64 s[26:27], -1
	v_readlane_b32 s77, v253, 6
	v_readlane_b32 s78, v253, 7
	v_readlane_b32 s79, v253, 8
	s_mov_b32 s72, s93
	s_mov_b32 s93, s16
	global_store_dwordx4 v[18:19], v[2:5], off offset:256
	s_cbranch_vccnz .LBB0_959
	s_andn2_b64 vcc, exec, s[0:1]
	s_cbranch_vccnz .LBB0_958
	s_barrier
	s_branch .LBB0_958
